# stack + RG-LRU unit prologue: 16 trickled conv/gate row loads issued with the first batch (renamed destinations, recounted vmcnt)
# baseline (speedup 1.0000x reference)
.LBB0_594:
	s_lshl_b32 s2, s37, 14
	s_and_b32 s2, s2, 0xc000
	s_or_b32 s8, s2, s36
	s_lshl_b32 s2, s37, 7
	s_ashr_i32 s14, s37, 7
	s_and_b32 s40, s2, 0x180
	s_mov_b32 s2, 0
	s_ashr_i32 s15, s14, 31
	s_bfe_u32 s39, s37, 0x50002
	s_ashr_i32 s3, s2, 31
	s_lshl_b32 s38, s39, 7
	s_lshl_b64 s[12:13], s[14:15], 12
	s_lshl_b64 s[2:3], s[2:3], 3
	s_add_u32 s2, s0, s2
	s_addc_u32 s3, s1, s3
	s_mov_b64 s[2:3], s[100:101]
	s_mov_b32 s6, 10
	s_mov_b32 s16, 14
	s_mov_b32 s18, 0
	s_mov_b32 s20, 0
	s_waitcnt lgkmcnt(0)
	s_add_u32 s2, s2, s81
	s_addc_u32 s3, s3, 0
	s_add_u32 s30, s2, 0x9600000
	s_mov_b32 s2, 9
	s_addc_u32 s31, s3, 0
	s_ashr_i32 s3, s2, 31
	s_lshl_b64 s[2:3], s[2:3], 3
	s_add_u32 s2, s0, s2
	s_addc_u32 s3, s1, s3
	s_load_dwordx2 s[2:3], s[2:3], 0x0
	s_mov_b32 s22, 0
	s_waitcnt vmcnt(13)
	v_mov_b32_e32 v56, v0
	v_mov_b32_e32 v7, v4
	s_waitcnt lgkmcnt(0)
	s_add_u32 s2, s2, s4
	s_addc_u32 s3, s3, s5
	s_ashr_i32 s7, s6, 31
	s_lshl_b64 s[6:7], s[6:7], 3
	s_add_u32 s6, s0, s6
	s_addc_u32 s7, s1, s7
	s_load_dwordx2 s[6:7], s[6:7], 0x0
	v_mov_b64_e32 v[46:47], s[30:31]
	v_mov_b32_e32 v49, v4
	v_mov_b32_e32 v19, v4
	v_mov_b32_e32 v21, v4
	s_waitcnt lgkmcnt(0)
	s_add_u32 s34, s6, s10
	s_mov_b32 s6, 0
	s_addc_u32 s35, s7, s11
	s_ashr_i32 s7, s6, 31
	s_lshl_b64 s[6:7], s[6:7], 3
	s_add_u32 s6, s0, s6
	s_addc_u32 s7, s1, s7
	s_mov_b64 s[6:7], s[100:101]
	s_lshl_b32 s15, s8, 1
	s_mov_b32 s8, 0
	v_mov_b32_e32 v23, v4
	s_waitcnt lgkmcnt(0)
	s_add_u32 s6, s6, s15
	s_addc_u32 s7, s7, 0
	s_ashr_i32 s9, s8, 31
	s_lshl_b64 s[8:9], s[8:9], 3
	s_add_u32 s8, s0, s8
	s_addc_u32 s9, s1, s9
	s_mov_b64 s[8:9], s[100:101]
	v_mov_b32_e32 v111, 1.0
	v_mov_b32_e32 v109, 0
	s_waitcnt lgkmcnt(0)
	s_add_u32 s24, s8, s15
	s_mov_b32 s8, 12
	s_addc_u32 s25, s9, 0
	s_ashr_i32 s9, s8, 31
	s_lshl_b64 s[8:9], s[8:9], 3
	s_add_u32 s8, s0, s8
	s_addc_u32 s9, s1, s9
	s_load_dwordx2 s[8:9], s[8:9], 0x0
	s_mov_b32 s15, 0
	s_waitcnt lgkmcnt(0)
	s_add_u32 s8, s8, s10
	s_addc_u32 s9, s9, s11
	s_ashr_i32 s17, s16, 31
	s_lshl_b64 s[16:17], s[16:17], 3
	s_add_u32 s16, s0, s16
	s_addc_u32 s17, s1, s17
	s_load_dwordx2 s[16:17], s[16:17], 0x0
	s_waitcnt lgkmcnt(0)
	s_add_u32 s26, s16, s10
	s_mov_b32 s16, 15
	s_addc_u32 s27, s17, s11
	s_ashr_i32 s17, s16, 31
	s_lshl_b64 s[16:17], s[16:17], 3
	s_add_u32 s16, s0, s16
	s_addc_u32 s17, s1, s17
	s_load_dwordx2 s[16:17], s[16:17], 0x0
	s_waitcnt lgkmcnt(0)
	s_add_u32 s28, s16, s10
	s_mov_b32 s16, 0
	s_addc_u32 s29, s17, s11
	s_ashr_i32 s17, s16, 31
	s_lshl_b64 s[16:17], s[16:17], 3
	s_add_u32 s16, s0, s16
	s_addc_u32 s17, s1, s17
	s_load_dwordx2 s[16:17], s[16:17], 0xd0
	s_ashr_i32 s19, s18, 31
	s_lshl_b64 s[18:19], s[18:19], 3
	s_add_u32 s18, s0, s18
	s_addc_u32 s19, s1, s19
	s_load_dwordx2 s[18:19], s[18:19], 0xd0
	s_ashr_i32 s21, s20, 31
	s_lshl_b64 s[20:21], s[20:21], 3
	s_add_u32 s20, s0, s20
	s_addc_u32 s21, s1, s21
	s_mov_b64 s[20:21], s[100:101]
	s_ashr_i32 s23, s22, 31
	s_lshl_b64 s[22:23], s[22:23], 3
	s_add_u32 s22, s0, s22
	s_addc_u32 s23, s1, s23
	s_mov_b64 s[22:23], s[100:101]
	s_waitcnt vmcnt(9)
	v_ashrrev_i32_e32 v70, 4, v56
	v_add_u32_e32 v54, s38, v70
	v_max_i32_e32 v3, 3, v54
	v_lshlrev_b32_e32 v2, 3, v56
	v_add_u32_e32 v6, -3, v3
	v_and_b32_e32 v2, 0x78, v2
	v_lshl_add_u64 v[6:7], s[12:13], 0, v[6:7]
	v_or_b32_e32 v2, s40, v2
	v_mad_u64_u32 v[8:9], s[30:31], v6, s77, v[46:47]
	v_mad_i32_i24 v9, v7, s77, v9
	v_lshlrev_b32_e32 v48, 1, v2
	v_lshlrev_b32_e32 v18, 2, v2
	v_lshl_add_u64 v[6:7], v[8:9], 0, v[48:49]
	v_max_i32_e32 v3, 2, v54
	global_load_dwordx4 v[34:37], v18, s[2:3]
	global_load_dwordx4 v[14:17], v18, s[2:3] offset:2048
	global_load_dwordx4 v[58:61], v[6:7], off offset:3072
	v_add_u32_e32 v6, -2, v3
	v_mov_b32_e32 v7, v4
	v_lshl_add_u64 v[6:7], s[12:13], 0, v[6:7]
	v_mad_u64_u32 v[8:9], s[30:31], v6, s77, v[46:47]
	v_mad_i32_i24 v9, v7, s77, v9
	v_lshl_add_u64 v[6:7], v[8:9], 0, v[48:49]
	global_load_dwordx4 v[62:65], v[6:7], off offset:3072
	global_load_dwordx4 v[26:29], v18, s[34:35]
	global_load_dwordx4 v[42:45], v18, s[2:3] offset:16
	s_nop 0
	global_load_dwordx4 v[6:9], v18, s[2:3] offset:2064
	global_load_dwordx4 v[10:13], v18, s[34:35] offset:16
	v_max_i32_e32 v5, 1, v54
	v_max_i32_e32 v22, 0, v54
	v_add_u32_e32 v20, -1, v5
	v_lshl_add_u64 v[18:19], s[2:3], 0, v[18:19]
	s_mov_b64 s[2:3], 0x1000
	v_lshl_add_u64 v[52:53], s[12:13], 0, v[22:23]
	v_lshl_add_u64 v[50:51], s[12:13], 0, v[20:21]
	v_lshl_add_u64 v[20:21], v[18:19], 0, s[2:3]
	v_add_co_u32_e32 v22, vcc, s88, v18
	s_mov_b64 s[2:3], 0x1800
	s_nop 0
	v_addc_co_u32_e32 v23, vcc, 0, v19, vcc
	v_lshl_add_u64 v[18:19], v[18:19], 0, s[2:3]
	v_mad_u64_u32 v[66:67], s[2:3], v50, s77, v[46:47]
	v_mad_i32_i24 v67, v51, s77, v67
	v_lshl_add_u64 v[50:51], v[66:67], 0, v[48:49]
	global_load_dwordx4 v[38:41], v[22:23], off
	global_load_dwordx4 v[30:33], v[20:21], off offset:16
	s_nop 0
	global_load_dwordx4 v[22:25], v[22:23], off offset:2048
	s_nop 0
	global_load_dwordx4 v[18:21], v[18:19], off offset:16
	v_cmp_lt_i32_e32 vcc, 2, v54
	global_load_dwordx4 v[66:69], v[50:51], off offset:3072
	v_mad_u64_u32 v[206:207], s[2:3], v52, s77, v[46:47]
	v_mad_i32_i24 v207, v53, s77, v207
	v_lshl_add_u64 v[206:207], v[206:207], 0, v[48:49]
	global_load_dwordx4 v[134:137], v[206:207], off offset:3072
	v_ashrrev_i32_e32 v207, 31, v54
	v_mov_b32_e32 v206, v54
	v_lshl_add_u64 v[208:209], s[12:13], 0, v[206:207]
	v_mad_u64_u32 v[210:211], s[2:3], v208, s77, v[46:47]
	v_mad_i32_i24 v211, v209, s77, v211
	v_lshl_add_u64 v[208:209], v[210:211], 0, v[48:49]
	v_add_co_u32_e64 v208, s[2:3], s88, v208
	s_nop 1
	v_addc_co_u32_e64 v209, s[2:3], 0, v209, s[2:3]
	global_load_dwordx4 v[138:141], v[208:209], off
	v_add_u32_e32 v206, 32, v70
	v_add_u32_e32 v208, s38, v206
	v_max_i32_e32 v209, 3, v208
	v_add_u32_e32 v210, -3, v209
	v_mov_b32_e32 v211, v4
	v_lshl_add_u64 v[210:211], s[12:13], 0, v[210:211]
	v_mad_u64_u32 v[212:213], s[2:3], v210, s77, v[46:47]
	v_mad_i32_i24 v213, v211, s77, v213
	v_lshl_add_u64 v[214:215], v[212:213], 0, v[48:49]
	global_load_dwordx4 v[142:145], v[214:215], off offset:3072
	v_add_u32_e32 v206, 32, v70
	v_add_u32_e32 v208, s38, v206
	v_max_i32_e32 v210, 2, v208
	v_add_u32_e32 v210, -2, v210
	v_mov_b32_e32 v211, v4
	v_lshl_add_u64 v[210:211], s[12:13], 0, v[210:211]
	v_mad_u64_u32 v[212:213], s[2:3], v210, s77, v[46:47]
	v_mad_i32_i24 v213, v211, s77, v213
	v_lshl_add_u64 v[210:211], v[212:213], 0, v[48:49]
	global_load_dwordx4 v[146:149], v[210:211], off offset:3072
	v_add_u32_e32 v206, 32, v70
	v_add_u32_e32 v208, s38, v206
	v_max_i32_e32 v210, 1, v208
	v_add_u32_e32 v210, -1, v210
	v_mov_b32_e32 v211, v4
	v_lshl_add_u64 v[210:211], s[12:13], 0, v[210:211]
	v_mad_u64_u32 v[212:213], s[2:3], v210, s77, v[46:47]
	v_mad_i32_i24 v213, v211, s77, v213
	v_lshl_add_u64 v[210:211], v[212:213], 0, v[48:49]
	global_load_dwordx4 v[150:153], v[210:211], off offset:3072
	v_add_u32_e32 v206, 32, v70
	v_add_u32_e32 v208, s38, v206
	v_max_i32_e32 v210, 0, v208
	v_mov_b32_e32 v211, v4
	v_lshl_add_u64 v[210:211], s[12:13], 0, v[210:211]
	v_mad_u64_u32 v[212:213], s[2:3], v210, s77, v[46:47]
	v_mad_i32_i24 v213, v211, s77, v213
	v_lshl_add_u64 v[210:211], v[212:213], 0, v[48:49]
	global_load_dwordx4 v[154:157], v[210:211], off offset:3072
	v_add_u32_e32 v206, 32, v70
	v_add_u32_e32 v208, s38, v206
	v_ashrrev_i32_e32 v209, 31, v208
	v_lshl_add_u64 v[210:211], s[12:13], 0, v[208:209]
	v_mad_u64_u32 v[212:213], s[2:3], v210, s77, v[46:47]
	v_mad_i32_i24 v213, v211, s77, v213
	v_lshl_add_u64 v[210:211], v[212:213], 0, v[48:49]
	v_add_co_u32_e64 v210, s[2:3], s88, v210
	s_nop 1
	v_addc_co_u32_e64 v211, s[2:3], 0, v211, s[2:3]
	global_load_dwordx4 v[158:161], v[210:211], off
	v_add_u32_e32 v206, 64, v70
	v_mov_b32_e32 v209, v4
	v_add_u32_e32 v210, s38, v206
	v_max_i32_e32 v213, 3, v210
	v_add_u32_e32 v208, -3, v213
	v_lshl_add_u64 v[208:209], s[12:13], 0, v[208:209]
	v_mad_u64_u32 v[214:215], s[2:3], v208, s77, v[46:47]
	v_mad_i32_i24 v215, v209, s77, v215
	v_lshl_add_u64 v[208:209], v[214:215], 0, v[48:49]
	global_load_dwordx4 v[162:165], v[208:209], off offset:3072
	v_add_u32_e32 v206, 64, v70
	v_add_u32_e32 v208, s38, v206
	v_max_i32_e32 v211, 2, v208
	v_add_u32_e32 v212, -2, v211
	v_mov_b32_e32 v213, v4
	v_lshl_add_u64 v[212:213], s[12:13], 0, v[212:213]
	v_mad_u64_u32 v[214:215], s[2:3], v212, s77, v[46:47]
	v_mad_i32_i24 v215, v213, s77, v215
	v_lshl_add_u64 v[212:213], v[214:215], 0, v[48:49]
	global_load_dwordx4 v[166:169], v[212:213], off offset:3072
	v_add_u32_e32 v206, 64, v70
	v_add_u32_e32 v208, s38, v206
	v_mov_b32_e32 v211, v4
	v_max_i32_e32 v210, 1, v208
	v_add_u32_e32 v210, -1, v210
	v_lshl_add_u64 v[210:211], s[12:13], 0, v[210:211]
	v_mad_u64_u32 v[212:213], s[2:3], v210, s77, v[46:47]
	v_mad_i32_i24 v213, v211, s77, v213
	v_lshl_add_u64 v[210:211], v[212:213], 0, v[48:49]
	global_load_dwordx4 v[170:173], v[210:211], off offset:3072
	v_add_u32_e32 v206, 64, v70
	v_add_u32_e32 v208, s38, v206
	v_max_i32_e32 v210, 0, v208
	v_mov_b32_e32 v211, v4
	v_lshl_add_u64 v[210:211], s[12:13], 0, v[210:211]
	v_mad_u64_u32 v[212:213], s[2:3], v210, s77, v[46:47]
	v_mad_i32_i24 v213, v211, s77, v213
	v_lshl_add_u64 v[210:211], v[212:213], 0, v[48:49]
	global_load_dwordx4 v[174:177], v[210:211], off offset:3072
	v_add_u32_e32 v206, 64, v70
	v_add_u32_e32 v208, s38, v206
	v_ashrrev_i32_e32 v209, 31, v208
	v_lshl_add_u64 v[210:211], s[12:13], 0, v[208:209]
	v_mad_u64_u32 v[212:213], s[2:3], v210, s77, v[46:47]
	v_mad_i32_i24 v213, v211, s77, v213
	v_lshl_add_u64 v[210:211], v[212:213], 0, v[48:49]
	v_add_co_u32_e64 v212, s[2:3], s88, v210
	s_nop 1
	v_addc_co_u32_e64 v213, s[2:3], 0, v211, s[2:3]
	global_load_dwordx4 v[178:181], v[212:213], off
	v_add_u32_e32 v206, 0x60, v70
	v_mov_b32_e32 v209, v4
	v_add_u32_e32 v210, s38, v206
	v_max_i32_e32 v213, 3, v210
	v_add_u32_e32 v208, -3, v213
	v_lshl_add_u64 v[208:209], s[12:13], 0, v[208:209]
	v_mad_u64_u32 v[214:215], s[2:3], v208, s77, v[46:47]
	v_mad_i32_i24 v215, v209, s77, v215
	v_lshl_add_u64 v[216:217], v[214:215], 0, v[48:49]
	global_load_dwordx4 v[182:185], v[216:217], off offset:3072
	v_add_u32_e32 v206, 0x60, v70
	v_add_u32_e32 v208, s38, v206
	v_mov_b32_e32 v211, v4
	v_max_i32_e32 v212, 1, v208
	v_add_u32_e32 v210, -1, v212
	v_lshl_add_u64 v[210:211], s[12:13], 0, v[210:211]
	v_mad_u64_u32 v[214:215], s[2:3], v210, s77, v[46:47]
	v_mad_i32_i24 v215, v211, s77, v215
	v_lshl_add_u64 v[210:211], v[214:215], 0, v[48:49]
	global_load_dwordx4 v[186:189], v[210:211], off offset:3072
	v_add_u32_e32 v206, 0x60, v70
	v_add_u32_e32 v208, s38, v206
	v_max_i32_e32 v210, 0, v208
	v_mov_b32_e32 v211, v4
	v_lshl_add_u64 v[210:211], s[12:13], 0, v[210:211]
	v_mad_u64_u32 v[212:213], s[2:3], v210, s77, v[46:47]
	v_mad_i32_i24 v213, v211, s77, v213
	v_lshl_add_u64 v[210:211], v[212:213], 0, v[48:49]
	global_load_dwordx4 v[190:193], v[210:211], off offset:3072
	v_add_u32_e32 v206, 0x60, v70
	v_add_u32_e32 v208, s38, v206
	v_ashrrev_i32_e32 v209, 31, v208
	v_lshl_add_u64 v[210:211], s[12:13], 0, v[208:209]
	v_mad_u64_u32 v[212:213], s[2:3], v210, s77, v[46:47]
	v_mad_i32_i24 v213, v211, s77, v213
	v_lshl_add_u64 v[210:211], v[212:213], 0, v[48:49]
	v_add_co_u32_e64 v210, s[2:3], s88, v210
	s_nop 1
	v_addc_co_u32_e64 v211, s[2:3], 0, v211, s[2:3]
	global_load_dwordx4 v[194:197], v[210:211], off
	v_xor_b32_e32 v3, v70, v56
	v_lshlrev_b32_e32 v3, 4, v3
	v_and_b32_e32 v3, 0xf0, v3
	v_add_u32_e32 v57, 0, v3
	s_waitcnt vmcnt(28)
	v_mov_b32_e32 v50, v34
	s_waitcnt vmcnt(27)
	v_mov_b32_e32 v51, v14
	s_waitcnt vmcnt(26)
	v_cndmask_b32_e32 v5, 0, v61, vcc
	v_cndmask_b32_e32 v55, 0, v60, vcc
	v_cndmask_b32_e32 v71, 0, v59, vcc
	v_cndmask_b32_e32 v58, 0, v58, vcc
	v_cmp_lt_i32_e32 vcc, 1, v54
	v_mov_b32_e32 v14, v35
	v_lshlrev_b32_e32 v34, 16, v58
	s_waitcnt vmcnt(25)
	v_cndmask_b32_e32 v59, 0, v62, vcc
	v_lshlrev_b32_e32 v35, 16, v59
	v_pk_mul_f32 v[34:35], v[50:51], v[34:35]
	v_cndmask_b32_e32 v72, 0, v63, vcc
	s_waitcnt vmcnt(24)
	v_add_f32_e32 v34, v26, v34
	v_add_f32_e32 v73, v34, v35
	v_mad_u64_u32 v[34:35], s[2:3], v52, s77, v[46:47]
	v_mad_i32_i24 v35, v53, s77, v35
	v_and_b32_e32 v63, 0xffff0000, v59
	v_and_b32_e32 v62, 0xffff0000, v58
	v_lshl_add_u64 v[34:35], v[34:35], 0, v[48:49]
	v_pk_mul_f32 v[34:35], v[14:15], v[62:63]
	v_mov_b32_e32 v52, v36
	v_add_f32_e32 v34, v27, v34
	v_add_f32_e32 v78, v34, v35
	v_lshlrev_b32_e32 v35, 16, v72
	v_lshlrev_b32_e32 v34, 16, v71
	v_mov_b32_e32 v53, v16
	v_pk_mul_f32 v[34:35], v[52:53], v[34:35]
	v_cndmask_b32_e32 v64, 0, v64, vcc
	v_add_f32_e32 v16, v28, v34
	v_add_f32_e32 v79, v16, v35
	v_and_b32_e32 v35, 0xffff0000, v72
	v_and_b32_e32 v34, 0xffff0000, v71
	v_mov_b32_e32 v16, v37
	v_pk_mul_f32 v[34:35], v[16:17], v[34:35]
	s_waitcnt vmcnt(23)
	v_mov_b32_e32 v36, v42
	v_add_f32_e32 v34, v29, v34
	v_add_f32_e32 v71, v34, v35
	v_lshlrev_b32_e32 v35, 16, v64
	v_lshlrev_b32_e32 v34, 16, v55
	s_waitcnt vmcnt(22)
	v_mov_b32_e32 v37, v6
	v_pk_mul_f32 v[34:35], v[36:37], v[34:35]
	v_cndmask_b32_e32 v65, 0, v65, vcc
	s_waitcnt vmcnt(21)
	v_add_f32_e32 v6, v10, v34
	v_add_f32_e32 v80, v6, v35
	v_and_b32_e32 v35, 0xffff0000, v64
	v_and_b32_e32 v34, 0xffff0000, v55
	v_mov_b32_e32 v6, v43
	v_pk_mul_f32 v[34:35], v[6:7], v[34:35]
	v_lshlrev_b32_e32 v43, 16, v65
	v_add_f32_e32 v34, v11, v34
	v_add_f32_e32 v81, v34, v35
	v_lshlrev_b32_e32 v42, 16, v5
	v_mov_b32_e32 v34, v44
	v_mov_b32_e32 v35, v8
	v_pk_mul_f32 v[42:43], v[34:35], v[42:43]
	v_ashrrev_i32_e32 v55, 31, v54
	v_add_f32_e32 v8, v12, v42
	v_add_f32_e32 v82, v8, v43
	v_and_b32_e32 v43, 0xffff0000, v65
	v_and_b32_e32 v42, 0xffff0000, v5
	v_mov_b32_e32 v8, v45
	v_pk_mul_f32 v[42:43], v[8:9], v[42:43]
	v_add_u32_e32 v72, 32, v70
	v_add_f32_e32 v5, v13, v42
	v_add_f32_e32 v5, v5, v43
	v_lshl_add_u64 v[42:43], s[12:13], 0, v[54:55]
	v_mad_u64_u32 v[44:45], s[2:3], v42, s77, v[46:47]
	v_mad_i32_i24 v45, v43, s77, v45
	v_lshl_add_u64 v[42:43], v[44:45], 0, v[48:49]
	v_add_u32_e32 v44, s38, v72
	v_max_i32_e32 v45, 3, v44
	v_add_u32_e32 v62, -3, v45
	v_mov_b32_e32 v63, v4
	v_lshl_add_u64 v[62:63], s[12:13], 0, v[62:63]
	v_mad_u64_u32 v[64:65], s[2:3], v62, s77, v[46:47]
	v_add_co_u32_e32 v42, vcc, s88, v42
	v_mad_i32_i24 v65, v63, s77, v65
	s_nop 0
	v_addc_co_u32_e32 v43, vcc, 0, v43, vcc
	v_lshl_add_u64 v[74:75], v[64:65], 0, v[48:49]
	s_nop 0
	v_max_i32_e32 v42, 2, v44
	v_add_u32_e32 v42, -2, v42
	v_mov_b32_e32 v43, v4
	v_cmp_lt_i32_e32 vcc, 0, v54
	v_lshl_add_u64 v[42:43], s[12:13], 0, v[42:43]
	s_waitcnt vmcnt(16)
	v_cndmask_b32_e32 v84, 0, v67, vcc
	v_cndmask_b32_e32 v85, 0, v66, vcc
	v_mad_u64_u32 v[66:67], s[2:3], v42, s77, v[46:47]
	v_mad_i32_i24 v67, v43, s77, v67
	v_lshl_add_u64 v[42:43], v[66:67], 0, v[48:49]
	v_cndmask_b32_e32 v45, 0, v69, vcc
	v_cndmask_b32_e32 v83, 0, v68, vcc
	v_cmp_lt_i32_e32 vcc, -1, v54
	v_lshlrev_b32_e32 v54, 16, v85
	v_mov_b32_e32 v42, v38
	s_waitcnt vmcnt(15)
	v_cndmask_b32_e32 v58, 0, v134, vcc
	v_lshlrev_b32_e32 v55, 16, v58
	v_mov_b32_e32 v43, v22
	v_pk_mul_f32 v[54:55], v[42:43], v[54:55]
	v_cndmask_b32_e32 v59, 0, v135, vcc
	v_add_f32_e32 v22, v73, v54
	v_add_f32_e32 v73, v22, v55
	v_and_b32_e32 v55, 0xffff0000, v58
	v_and_b32_e32 v54, 0xffff0000, v85
	v_mov_b32_e32 v22, v39
	v_pk_mul_f32 v[38:39], v[22:23], v[54:55]
	v_lshlrev_b32_e32 v55, 16, v59
	v_add_f32_e32 v38, v78, v38
	v_add_f32_e32 v58, v38, v39
	v_lshlrev_b32_e32 v54, 16, v84
	v_mov_b32_e32 v38, v40
	v_mov_b32_e32 v39, v24
	v_pk_mul_f32 v[54:55], v[38:39], v[54:55]
	v_cndmask_b32_e32 v60, 0, v136, vcc
	v_add_f32_e32 v24, v79, v54
	v_add_f32_e32 v78, v24, v55
	v_and_b32_e32 v55, 0xffff0000, v59
	v_and_b32_e32 v54, 0xffff0000, v84
	v_mov_b32_e32 v24, v41
	v_pk_mul_f32 v[40:41], v[24:25], v[54:55]
	v_lshlrev_b32_e32 v55, 16, v60
	v_add_f32_e32 v40, v71, v40
	v_add_f32_e32 v59, v40, v41
	v_lshlrev_b32_e32 v54, 16, v83
	v_mov_b32_e32 v40, v30
	v_mov_b32_e32 v41, v18
	v_pk_mul_f32 v[54:55], v[40:41], v[54:55]
	v_cndmask_b32_e32 v61, 0, v137, vcc
	v_add_f32_e32 v18, v80, v54
	v_add_f32_e32 v71, v18, v55
	v_and_b32_e32 v55, 0xffff0000, v60
	v_and_b32_e32 v54, 0xffff0000, v83
	v_mov_b32_e32 v18, v31
	v_pk_mul_f32 v[30:31], v[18:19], v[54:55]
	v_lshlrev_b32_e32 v55, 16, v61
	v_add_f32_e32 v30, v81, v30
	v_add_f32_e32 v60, v30, v31
	v_lshlrev_b32_e32 v54, 16, v45
	v_mov_b32_e32 v30, v32
	v_mov_b32_e32 v31, v20
	v_pk_mul_f32 v[54:55], v[30:31], v[54:55]
	v_cvt_pk_bf16_f32 v58, v73, v58
	v_cvt_pk_bf16_f32 v59, v78, v59
	v_cvt_pk_bf16_f32 v60, v71, v60
	v_cmp_lt_i32_e32 vcc, 2, v44
	v_add_f32_e32 v20, v82, v54
	v_add_f32_e32 v79, v20, v55
	v_and_b32_e32 v55, 0xffff0000, v61
	v_and_b32_e32 v54, 0xffff0000, v45
	v_mov_b32_e32 v20, v33
	v_pk_mul_f32 v[32:33], v[20:21], v[54:55]
	s_waitcnt vmcnt(13)
	v_cndmask_b32_e32 v71, 0, v145, vcc
	v_add_f32_e32 v5, v5, v32
	v_add_f32_e32 v5, v5, v33
	v_cvt_pk_bf16_f32 v61, v79, v5
	v_lshlrev_b32_e32 v5, 8, v70
	v_add_u32_e32 v32, v57, v5
	ds_write_b128 v32, v[58:61]
	ds_write_b128 v32, v[138:141] offset:32768
	v_max_i32_e32 v32, 1, v44
	v_add_u32_e32 v32, -1, v32
	v_mov_b32_e32 v33, v4
	v_lshl_add_u64 v[32:33], s[12:13], 0, v[32:33]
	v_mad_u64_u32 v[54:55], s[2:3], v32, s77, v[46:47]
	v_mad_i32_i24 v55, v33, s77, v55
	v_lshl_add_u64 v[32:33], v[54:55], 0, v[48:49]
	v_max_i32_e32 v32, 0, v44
	v_mov_b32_e32 v33, v4
	v_lshl_add_u64 v[32:33], s[12:13], 0, v[32:33]
	v_mad_u64_u32 v[54:55], s[2:3], v32, s77, v[46:47]
	v_mad_i32_i24 v55, v33, s77, v55
	v_lshl_add_u64 v[32:33], v[54:55], 0, v[48:49]
	v_cndmask_b32_e32 v45, 0, v144, vcc
	v_cndmask_b32_e32 v73, 0, v143, vcc
	v_cndmask_b32_e32 v74, 0, v142, vcc
	v_cmp_lt_i32_e32 vcc, 1, v44
	v_lshlrev_b32_e32 v32, 16, v74
	s_waitcnt vmcnt(12)
	v_cndmask_b32_e32 v55, 0, v146, vcc
	v_lshlrev_b32_e32 v33, 16, v55
	v_pk_mul_f32 v[32:33], v[50:51], v[32:33]
	v_cndmask_b32_e32 v54, 0, v147, vcc
	v_add_f32_e32 v32, v26, v32
	v_add_f32_e32 v84, v32, v33
	v_and_b32_e32 v33, 0xffff0000, v55
	v_and_b32_e32 v32, 0xffff0000, v74
	v_pk_mul_f32 v[32:33], v[14:15], v[32:33]
	v_cndmask_b32_e32 v68, 0, v148, vcc
	v_add_f32_e32 v32, v27, v32
	v_add_f32_e32 v85, v32, v33
	v_lshlrev_b32_e32 v33, 16, v54
	v_lshlrev_b32_e32 v32, 16, v73
	v_pk_mul_f32 v[32:33], v[52:53], v[32:33]
	v_cndmask_b32_e32 v75, 0, v149, vcc
	v_add_f32_e32 v32, v28, v32
	v_add_f32_e32 v86, v32, v33
	v_and_b32_e32 v33, 0xffff0000, v54
	v_and_b32_e32 v32, 0xffff0000, v73
	v_pk_mul_f32 v[32:33], v[16:17], v[32:33]
	v_add_u32_e32 v74, 64, v70
	v_add_f32_e32 v32, v29, v32
	v_add_f32_e32 v73, v32, v33
	v_lshlrev_b32_e32 v33, 16, v68
	v_lshlrev_b32_e32 v32, 16, v45
	v_pk_mul_f32 v[32:33], v[36:37], v[32:33]
	s_nop 0
	v_add_f32_e32 v32, v10, v32
	v_add_f32_e32 v87, v32, v33
	v_and_b32_e32 v32, 0xffff0000, v45
	v_ashrrev_i32_e32 v45, 31, v44
	v_lshl_add_u64 v[54:55], s[12:13], 0, v[44:45]
	v_mad_u64_u32 v[66:67], s[2:3], v54, s77, v[46:47]
	v_mad_i32_i24 v67, v55, s77, v67
	v_lshl_add_u64 v[54:55], v[66:67], 0, v[48:49]
	v_add_co_u32_e32 v54, vcc, s88, v54
	v_and_b32_e32 v33, 0xffff0000, v68
	s_nop 0
	v_addc_co_u32_e32 v55, vcc, 0, v55, vcc
	v_pk_mul_f32 v[32:33], v[6:7], v[32:33]
	v_mov_b32_e32 v55, v4
	v_add_f32_e32 v32, v11, v32
	v_add_f32_e32 v88, v32, v33
	v_lshlrev_b32_e32 v33, 16, v75
	v_lshlrev_b32_e32 v32, 16, v71
	v_pk_mul_f32 v[32:33], v[34:35], v[32:33]
	v_cmp_lt_i32_e32 vcc, 0, v44
	v_add_f32_e32 v89, v12, v32
	v_add_u32_e32 v32, s38, v74
	v_max_i32_e32 v45, 3, v32
	v_add_u32_e32 v54, -3, v45
	v_lshl_add_u64 v[54:55], s[12:13], 0, v[54:55]
	v_mad_u64_u32 v[76:77], s[2:3], v54, s77, v[46:47]
	v_mad_i32_i24 v77, v55, s77, v77
	v_lshl_add_u64 v[54:55], v[76:77], 0, v[48:49]
	v_max_i32_e32 v45, 2, v32
	v_add_u32_e32 v54, -2, v45
	v_mov_b32_e32 v55, v4
	v_lshl_add_u64 v[54:55], s[12:13], 0, v[54:55]
	v_mad_u64_u32 v[80:81], s[2:3], v54, s77, v[46:47]
	v_mad_i32_i24 v81, v55, s77, v81
	v_lshl_add_u64 v[54:55], v[80:81], 0, v[48:49]
	v_and_b32_e32 v55, 0xffff0000, v75
	v_and_b32_e32 v54, 0xffff0000, v71
	v_pk_mul_f32 v[54:55], v[8:9], v[54:55]
	s_waitcnt vmcnt(11)
	v_cndmask_b32_e32 v75, 0, v153, vcc
	v_add_f32_e32 v45, v13, v54
	v_add_f32_e32 v71, v45, v55
	v_cndmask_b32_e32 v54, 0, v152, vcc
	v_cndmask_b32_e32 v55, 0, v151, vcc
	v_cndmask_b32_e32 v58, 0, v150, vcc
	v_cmp_lt_i32_e32 vcc, -1, v44
	v_lshlrev_b32_e32 v44, 16, v58
	v_add_f32_e32 v33, v89, v33
	s_waitcnt vmcnt(10)
	v_cndmask_b32_e32 v61, 0, v154, vcc
	v_lshlrev_b32_e32 v45, 16, v61
	v_pk_mul_f32 v[44:45], v[42:43], v[44:45]
	v_cndmask_b32_e32 v60, 0, v155, vcc
	v_add_f32_e32 v44, v84, v44
	v_add_f32_e32 v62, v44, v45
	v_and_b32_e32 v45, 0xffff0000, v61
	v_and_b32_e32 v44, 0xffff0000, v58
	v_pk_mul_f32 v[44:45], v[22:23], v[44:45]
	v_cndmask_b32_e32 v59, 0, v156, vcc
	v_add_f32_e32 v44, v85, v44
	v_add_f32_e32 v63, v44, v45
	v_lshlrev_b32_e32 v45, 16, v60
	v_lshlrev_b32_e32 v44, 16, v55
	v_pk_mul_f32 v[44:45], v[38:39], v[44:45]
	v_cndmask_b32_e32 v65, 0, v157, vcc
	v_add_f32_e32 v44, v86, v44
	v_add_f32_e32 v64, v44, v45
	v_and_b32_e32 v45, 0xffff0000, v60
	v_and_b32_e32 v44, 0xffff0000, v55
	v_pk_mul_f32 v[44:45], v[24:25], v[44:45]
	v_mov_b32_e32 v55, v4
	v_add_f32_e32 v44, v73, v44
	v_add_f32_e32 v73, v44, v45
	v_lshlrev_b32_e32 v45, 16, v59
	v_lshlrev_b32_e32 v44, 16, v54
	v_pk_mul_f32 v[44:45], v[40:41], v[44:45]
	v_cvt_pk_bf16_f32 v62, v62, v63
	v_cvt_pk_bf16_f32 v63, v64, v73
	v_lshlrev_b32_e32 v73, 8, v72
	v_add_f32_e32 v44, v87, v44
	v_add_f32_e32 v84, v44, v45
	v_and_b32_e32 v44, 0xffff0000, v54
	v_max_i32_e32 v54, 1, v32
	v_add_u32_e32 v54, -1, v54
	v_lshl_add_u64 v[54:55], s[12:13], 0, v[54:55]
	v_and_b32_e32 v45, 0xffff0000, v59
	v_mad_u64_u32 v[58:59], s[2:3], v54, s77, v[46:47]
	v_pk_mul_f32 v[44:45], v[18:19], v[44:45]
	v_mad_i32_i24 v59, v55, s77, v59
	v_lshl_add_u64 v[54:55], v[58:59], 0, v[48:49]
	v_add_f32_e32 v44, v88, v44
	v_add_f32_e32 v54, v44, v45
	v_lshlrev_b32_e32 v45, 16, v65
	v_lshlrev_b32_e32 v44, 16, v75
	v_pk_mul_f32 v[44:45], v[30:31], v[44:45]
	v_cvt_pk_bf16_f32 v64, v84, v54
	v_cmp_lt_i32_e32 vcc, 2, v32
	v_add_f32_e32 v33, v33, v44
	v_add_f32_e32 v33, v33, v45
	v_and_b32_e32 v45, 0xffff0000, v65
	v_and_b32_e32 v44, 0xffff0000, v75
	v_pk_mul_f32 v[44:45], v[20:21], v[44:45]
	s_nop 0
	v_add_f32_e32 v44, v71, v44
	v_add_f32_e32 v44, v44, v45
	v_cvt_pk_bf16_f32 v65, v33, v44
	v_max_i32_e32 v44, 0, v32
	v_mov_b32_e32 v45, v4
	v_lshl_add_u64 v[44:45], s[12:13], 0, v[44:45]
	v_mad_u64_u32 v[54:55], s[2:3], v44, s77, v[46:47]
	v_add_u32_e32 v33, v57, v73
	v_mad_i32_i24 v55, v45, s77, v55
	ds_write_b128 v33, v[62:65]
	s_waitcnt vmcnt(9)
	ds_write_b128 v33, v[158:161] offset:32768
	v_lshl_add_u64 v[44:45], v[54:55], 0, v[48:49]
	s_waitcnt vmcnt(8)
	v_cndmask_b32_e32 v33, 0, v165, vcc
	v_cndmask_b32_e32 v66, 0, v164, vcc
	v_cndmask_b32_e32 v67, 0, v163, vcc
	v_cndmask_b32_e32 v68, 0, v162, vcc
	v_cmp_lt_i32_e32 vcc, 1, v32
	v_lshlrev_b32_e32 v44, 16, v68
	v_add_u32_e32 v76, 0x60, v70
	s_waitcnt vmcnt(7)
	v_cndmask_b32_e32 v55, 0, v166, vcc
	v_lshlrev_b32_e32 v45, 16, v55
	v_pk_mul_f32 v[44:45], v[50:51], v[44:45]
	v_cndmask_b32_e32 v54, 0, v167, vcc
	v_add_f32_e32 v44, v26, v44
	v_add_f32_e32 v75, v44, v45
	v_and_b32_e32 v45, 0xffff0000, v55
	v_and_b32_e32 v44, 0xffff0000, v68
	v_pk_mul_f32 v[44:45], v[14:15], v[44:45]
	v_cndmask_b32_e32 v71, 0, v168, vcc
	v_add_f32_e32 v44, v27, v44
	v_add_f32_e32 v77, v44, v45
	v_lshlrev_b32_e32 v45, 16, v54
	v_lshlrev_b32_e32 v44, 16, v67
	v_pk_mul_f32 v[44:45], v[52:53], v[44:45]
	v_cndmask_b32_e32 v69, 0, v169, vcc
	v_add_f32_e32 v44, v28, v44
	v_add_f32_e32 v86, v44, v45
	v_and_b32_e32 v45, 0xffff0000, v54
	v_and_b32_e32 v44, 0xffff0000, v67
	v_pk_mul_f32 v[44:45], v[16:17], v[44:45]
	v_mov_b32_e32 v67, v4
	v_add_f32_e32 v44, v29, v44
	v_add_f32_e32 v87, v44, v45
	v_lshlrev_b32_e32 v45, 16, v71
	v_lshlrev_b32_e32 v44, 16, v66
	v_pk_mul_f32 v[44:45], v[36:37], v[44:45]
	v_cmp_lt_i32_e32 vcc, 0, v32
	v_add_f32_e32 v44, v10, v44
	v_add_f32_e32 v88, v44, v45
	v_and_b32_e32 v45, 0xffff0000, v71
	v_and_b32_e32 v44, 0xffff0000, v66
	v_pk_mul_f32 v[44:45], v[6:7], v[44:45]
	s_waitcnt vmcnt(6)
	v_cndmask_b32_e32 v91, 0, v173, vcc
	v_add_f32_e32 v44, v11, v44
	v_add_f32_e32 v71, v44, v45
	v_lshlrev_b32_e32 v45, 16, v69
	v_lshlrev_b32_e32 v44, 16, v33
	v_pk_mul_f32 v[44:45], v[34:35], v[44:45]
	s_nop 0
	v_add_f32_e32 v44, v12, v44
	v_add_f32_e32 v89, v44, v45
	v_and_b32_e32 v45, 0xffff0000, v69
	v_and_b32_e32 v44, 0xffff0000, v33
	v_pk_mul_f32 v[44:45], v[8:9], v[44:45]
	s_nop 0
	v_add_f32_e32 v33, v13, v44
	v_add_f32_e32 v90, v33, v45
	v_ashrrev_i32_e32 v33, 31, v32
	v_lshl_add_u64 v[44:45], s[12:13], 0, v[32:33]
	v_mad_u64_u32 v[54:55], s[2:3], v44, s77, v[46:47]
	v_mad_i32_i24 v55, v45, s77, v55
	v_lshl_add_u64 v[44:45], v[54:55], 0, v[48:49]
	v_add_co_u32_e64 v54, s[2:3], s88, v44
	v_add_u32_e32 v44, s38, v76
	v_max_i32_e32 v33, 3, v44
	v_add_u32_e32 v66, -3, v33
	v_lshl_add_u64 v[66:67], s[12:13], 0, v[66:67]
	v_addc_co_u32_e64 v55, s[2:3], 0, v45, s[2:3]
	v_mad_u64_u32 v[68:69], s[2:3], v66, s77, v[46:47]
	v_mad_i32_i24 v69, v67, s77, v69
	v_lshl_add_u64 v[78:79], v[68:69], 0, v[48:49]
	v_max_i32_e32 v33, 2, v44
	s_nop 0
	v_add_u32_e32 v54, -2, v33
	v_mov_b32_e32 v55, v4
	v_lshl_add_u64 v[54:55], s[12:13], 0, v[54:55]
	v_mad_u64_u32 v[82:83], s[2:3], v54, s77, v[46:47]
	v_mad_i32_i24 v83, v55, s77, v83
	v_lshl_add_u64 v[54:55], v[82:83], 0, v[48:49]
	global_load_dwordx4 v[82:85], v[54:55], off offset:3072
	v_cndmask_b32_e32 v45, 0, v172, vcc
	v_cndmask_b32_e32 v54, 0, v171, vcc
	v_cndmask_b32_e32 v55, 0, v170, vcc
	v_cmp_lt_i32_e32 vcc, -1, v32
	v_lshlrev_b32_e32 v32, 16, v55
	s_waitcnt vmcnt(6)
	v_cndmask_b32_e32 v61, 0, v174, vcc
	v_lshlrev_b32_e32 v33, 16, v61
	v_pk_mul_f32 v[32:33], v[42:43], v[32:33]
	v_cndmask_b32_e32 v60, 0, v175, vcc
	v_add_f32_e32 v32, v75, v32
	v_add_f32_e32 v75, v32, v33
	v_and_b32_e32 v33, 0xffff0000, v61
	v_and_b32_e32 v32, 0xffff0000, v55
	v_pk_mul_f32 v[32:33], v[22:23], v[32:33]
	v_cndmask_b32_e32 v59, 0, v176, vcc
	v_add_f32_e32 v32, v77, v32
	v_add_f32_e32 v77, v32, v33
	v_lshlrev_b32_e32 v33, 16, v60
	v_lshlrev_b32_e32 v32, 16, v54
	v_pk_mul_f32 v[32:33], v[38:39], v[32:33]
	v_cndmask_b32_e32 v58, 0, v177, vcc
	v_add_f32_e32 v32, v86, v32
	v_add_f32_e32 v92, v32, v33
	v_and_b32_e32 v33, 0xffff0000, v60
	v_and_b32_e32 v32, 0xffff0000, v54
	v_pk_mul_f32 v[32:33], v[24:25], v[32:33]
	v_mov_b32_e32 v55, v4
	v_add_f32_e32 v32, v87, v32
	v_add_f32_e32 v87, v32, v33
	v_lshlrev_b32_e32 v33, 16, v59
	v_lshlrev_b32_e32 v32, 16, v45
	v_pk_mul_f32 v[32:33], v[40:41], v[32:33]
	v_cvt_pk_bf16_f32 v86, v75, v77
	v_lshlrev_b32_e32 v75, 8, v74
	v_add_f32_e32 v32, v88, v32
	v_add_f32_e32 v88, v32, v33
	v_and_b32_e32 v33, 0xffff0000, v59
	v_and_b32_e32 v32, 0xffff0000, v45
	v_pk_mul_f32 v[32:33], v[18:19], v[32:33]
	v_cvt_pk_bf16_f32 v87, v92, v87
	v_cmp_lt_i32_e32 vcc, 2, v44
	v_add_f32_e32 v32, v71, v32
	v_add_f32_e32 v45, v32, v33
	v_lshlrev_b32_e32 v33, 16, v58
	v_lshlrev_b32_e32 v32, 16, v91
	v_pk_mul_f32 v[32:33], v[30:31], v[32:33]
	v_cvt_pk_bf16_f32 v88, v88, v45
	v_lshlrev_b32_e32 v77, 8, v76
	v_add_f32_e32 v32, v89, v32
	v_add_f32_e32 v71, v32, v33
	v_max_i32_e32 v32, 1, v44
	v_add_u32_e32 v54, -1, v32
	v_lshl_add_u64 v[54:55], s[12:13], 0, v[54:55]
	v_and_b32_e32 v33, 0xffff0000, v58
	v_mad_u64_u32 v[58:59], s[2:3], v54, s77, v[46:47]
	v_mad_i32_i24 v59, v55, s77, v59
	v_lshl_add_u64 v[54:55], v[58:59], 0, v[48:49]
	v_max_i32_e32 v54, 0, v44
	v_mov_b32_e32 v55, v4
	v_lshl_add_u64 v[54:55], s[12:13], 0, v[54:55]
	v_mad_u64_u32 v[62:63], s[2:3], v54, s77, v[46:47]
	v_mad_i32_i24 v63, v55, s77, v63
	v_lshl_add_u64 v[54:55], v[62:63], 0, v[48:49]
	v_and_b32_e32 v32, 0xffff0000, v91
	v_pk_mul_f32 v[32:33], v[20:21], v[32:33]
	s_waitcnt vmcnt(4)
	v_cndmask_b32_e32 v54, 0, v185, vcc
	v_add_f32_e32 v32, v90, v32
	v_add_f32_e32 v32, v32, v33
	v_cvt_pk_bf16_f32 v89, v71, v32
	v_add_u32_e32 v32, v57, v75
	ds_write_b128 v32, v[86:89]
	ds_write_b128 v32, v[178:181] offset:32768
	v_cndmask_b32_e32 v55, 0, v184, vcc
	v_cndmask_b32_e32 v45, 0, v183, vcc
	v_cndmask_b32_e32 v66, 0, v182, vcc
	v_cmp_lt_i32_e32 vcc, 1, v44
	v_lshlrev_b32_e32 v32, 16, v66
	s_waitcnt vmcnt(0)
	v_cndmask_b32_e32 v71, 0, v82, vcc
	v_lshlrev_b32_e32 v33, 16, v71
	v_pk_mul_f32 v[32:33], v[50:51], v[32:33]
	v_cndmask_b32_e32 v69, 0, v83, vcc
	v_add_f32_e32 v26, v26, v32
	v_add_f32_e32 v50, v26, v33
	v_and_b32_e32 v33, 0xffff0000, v71
	v_and_b32_e32 v32, 0xffff0000, v66
	v_pk_mul_f32 v[14:15], v[14:15], v[32:33]
	v_cndmask_b32_e32 v68, 0, v84, vcc
	v_add_f32_e32 v14, v27, v14
	v_add_f32_e32 v32, v14, v15
	v_lshlrev_b32_e32 v15, 16, v69
	v_lshlrev_b32_e32 v14, 16, v45
	v_pk_mul_f32 v[14:15], v[52:53], v[14:15]
	v_cndmask_b32_e32 v67, 0, v85, vcc
	v_add_f32_e32 v14, v28, v14
	v_add_f32_e32 v28, v14, v15
	v_and_b32_e32 v15, 0xffff0000, v69
	v_and_b32_e32 v14, 0xffff0000, v45
	v_pk_mul_f32 v[14:15], v[16:17], v[14:15]
	v_ashrrev_i32_e32 v45, 31, v44
	v_add_f32_e32 v14, v29, v14
	v_add_f32_e32 v29, v14, v15
	v_lshlrev_b32_e32 v15, 16, v68
	v_lshlrev_b32_e32 v14, 16, v55
	v_pk_mul_f32 v[14:15], v[36:37], v[14:15]
	v_and_b32_e32 v27, 0xffff0000, v68
	v_add_f32_e32 v10, v10, v14
	v_add_f32_e32 v10, v10, v15
	v_lshl_add_u64 v[14:15], s[12:13], 0, v[44:45]
	v_mad_u64_u32 v[16:17], s[2:3], v14, s77, v[46:47]
	v_mad_i32_i24 v17, v15, s77, v17
	v_lshl_add_u64 v[14:15], v[16:17], 0, v[48:49]
	v_add_co_u32_e32 v14, vcc, s88, v14
	v_and_b32_e32 v26, 0xffff0000, v55
	s_nop 0
	v_addc_co_u32_e32 v15, vcc, 0, v15, vcc
	v_pk_mul_f32 v[6:7], v[6:7], v[26:27]
	v_add_f32_e32 v6, v11, v6
	v_add_f32_e32 v11, v6, v7
	v_lshlrev_b32_e32 v7, 16, v67
	v_lshlrev_b32_e32 v6, 16, v54
	v_pk_mul_f32 v[6:7], v[34:35], v[6:7]
	v_cmp_lt_i32_e32 vcc, 0, v44
	v_add_f32_e32 v6, v12, v6
	v_add_f32_e32 v12, v6, v7
	v_and_b32_e32 v7, 0xffff0000, v67
	v_and_b32_e32 v6, 0xffff0000, v54
	v_pk_mul_f32 v[6:7], v[8:9], v[6:7]
	v_bfe_u32 v54, v56, 4, 2
	v_add_f32_e32 v6, v13, v6
	v_add_f32_e32 v13, v6, v7
	v_ashrrev_i32_e32 v6, 2, v56
	v_bfi_b32 v47, -16, v6, v56
	v_add_u32_e32 v78, s40, v47
	v_ashrrev_i32_e32 v79, 31, v78
	s_waitcnt vmcnt(0)
	v_cndmask_b32_e32 v26, 0, v189, vcc
	v_cndmask_b32_e32 v27, 0, v188, vcc
	v_cndmask_b32_e32 v33, 0, v187, vcc
	v_cndmask_b32_e32 v34, 0, v186, vcc
	v_cmp_lt_i32_e32 vcc, -1, v44
	v_lshlrev_b64 v[44:45], 2, v[78:79]
	v_lshl_add_u64 v[8:9], s[28:29], 0, v[44:45]
	global_load_dword v48, v[8:9], off
	s_waitcnt vmcnt(1)
	v_cndmask_b32_e32 v46, 0, v190, vcc
	v_lshlrev_b32_e32 v7, 16, v46
	v_lshlrev_b32_e32 v6, 16, v34
	v_pk_mul_f32 v[6:7], v[42:43], v[6:7]
	v_cndmask_b32_e32 v37, 0, v191, vcc
	v_add_f32_e32 v6, v50, v6
	v_add_f32_e32 v8, v6, v7
	v_and_b32_e32 v7, 0xffff0000, v46
	v_and_b32_e32 v6, 0xffff0000, v34
	v_pk_mul_f32 v[6:7], v[22:23], v[6:7]
	v_cndmask_b32_e32 v36, 0, v192, vcc
	v_add_f32_e32 v6, v32, v6
	v_add_f32_e32 v9, v6, v7
	v_lshlrev_b32_e32 v7, 16, v37
	v_lshlrev_b32_e32 v6, 16, v33
	v_pk_mul_f32 v[6:7], v[38:39], v[6:7]
	v_cndmask_b32_e32 v35, 0, v193, vcc
	v_add_f32_e32 v6, v28, v6
	v_add_f32_e32 v22, v6, v7
	v_and_b32_e32 v7, 0xffff0000, v37
	v_and_b32_e32 v6, 0xffff0000, v33
	v_pk_mul_f32 v[6:7], v[24:25], v[6:7]
	s_mov_b64 s[2:3], 0x600000
	v_add_f32_e32 v6, v29, v6
	v_add_f32_e32 v23, v6, v7
	v_lshlrev_b32_e32 v7, 16, v36
	v_lshlrev_b32_e32 v6, 16, v27
	v_pk_mul_f32 v[6:7], v[40:41], v[6:7]
	v_lshl_add_u64 v[38:39], s[8:9], 0, v[44:45]
	v_add_f32_e32 v6, v10, v6
	v_add_f32_e32 v10, v6, v7
	v_and_b32_e32 v7, 0xffff0000, v36
	v_and_b32_e32 v6, 0xffff0000, v27
	v_pk_mul_f32 v[6:7], v[18:19], v[6:7]
	v_lshlrev_b32_e32 v63, 10, v54
	v_add_f32_e32 v6, v11, v6
	v_add_f32_e32 v11, v6, v7
	v_lshlrev_b32_e32 v7, 16, v35
	v_lshlrev_b32_e32 v6, 16, v26
	v_pk_mul_f32 v[6:7], v[30:31], v[6:7]
	v_lshlrev_b32_e32 v64, 6, v54
	v_add_f32_e32 v6, v12, v6
	v_add_f32_e32 v12, v6, v7
	v_and_b32_e32 v7, 0xffff0000, v35
	v_and_b32_e32 v6, 0xffff0000, v26
	v_pk_mul_f32 v[6:7], v[20:21], v[6:7]
	v_and_b32_e32 v46, 15, v56
	v_add_f32_e32 v6, v13, v6
	v_add_f32_e32 v13, v6, v7
	v_cvt_pk_bf16_f32 v6, v8, v9
	v_cvt_pk_bf16_f32 v7, v22, v23
	v_cvt_pk_bf16_f32 v8, v10, v11
	v_cvt_pk_bf16_f32 v9, v12, v13
	v_add_u32_e32 v10, v57, v77
	ds_write_b128 v10, v[6:9]
	s_waitcnt vmcnt(1)
	ds_write_b128 v10, v[194:197] offset:32768
	v_lshlrev_b32_e32 v6, 7, v47
	v_ashrrev_i32_e32 v7, 31, v6
	v_lshlrev_b64 v[6:7], 1, v[6:7]
	v_lshl_add_u64 v[8:9], s[6:7], 0, v[6:7]
	v_lshlrev_b32_e32 v10, 4, v54
	v_mov_b32_e32 v11, v4
	v_lshl_add_u64 v[8:9], v[8:9], 0, v[10:11]
	v_lshl_add_u64 v[6:7], s[24:25], 0, v[6:7]
	v_lshl_add_u64 v[30:31], v[8:9], 0, s[2:3]
	v_lshl_add_u64 v[10:11], v[6:7], 0, v[10:11]
	s_mov_b64 s[2:3], 0x620000
	v_lshl_add_u64 v[34:35], v[10:11], 0, s[2:3]
	s_mov_b32 s2, 0x600000
	v_add_co_u32_e32 v6, vcc, s2, v8
	s_mov_b32 s2, 0x620000
	s_nop 0
	v_addc_co_u32_e32 v7, vcc, 0, v9, vcc
	v_add_co_u32_e32 v10, vcc, s2, v10
	global_load_dwordx4 v[6:9], v[6:7], off
	s_nop 0
	v_addc_co_u32_e32 v11, vcc, 0, v11, vcc
	global_load_dwordx4 v[10:13], v[10:11], off
	s_nop 0
	global_load_dwordx4 v[14:17], v[30:31], off offset:64
	global_load_dwordx4 v[18:21], v[30:31], off offset:128
	global_load_dwordx4 v[22:25], v[34:35], off offset:64
	global_load_dwordx4 v[26:29], v[34:35], off offset:128
	s_nop 0
	global_load_dwordx4 v[30:33], v[30:31], off offset:192
	s_nop 0
	global_load_dwordx4 v[34:37], v[34:35], off offset:192
	v_lshlrev_b32_e32 v47, 1, v47
	global_load_dword v71, v[38:39], off
	s_waitcnt vmcnt(9)
	v_mul_f32_e32 v38, 0xbfb8aa3b, v48
	v_exp_f32_e32 v41, v38
	v_lshl_add_u64 v[38:39], s[26:27], 0, v[44:45]
	global_load_dword v96, v[38:39], off
	v_lshlrev_b32_e32 v48, 1, v56
	v_and_b32_e32 v97, -16, v47
	v_and_b32_e32 v61, 14, v48
	v_xad_u32 v47, v97, v64, v63
	v_lshrrev_b32_e32 v40, 4, v56
	v_lshlrev_b32_e32 v62, 2, v54
	v_or_b32_e32 v47, v47, v61
	v_bitop3_b32 v38, v40, v46, 3 bitop3:0x6c
	v_add_u32_e32 v98, 0, v47
	v_or_b32_e32 v47, 1, v62
	v_lshlrev_b32_e32 v56, 8, v46
	v_lshlrev_b32_e32 v57, 4, v38
	v_bitop3_b32 v38, v54, v46, 4 bitop3:0x36
	v_bitop3_b32 v39, v54, v46, 8 bitop3:0x36
	v_lshlrev_b32_e32 v48, 8, v47
	v_lshlrev_b32_e32 v47, 4, v47
	v_add_u32_e32 v49, 0, v56
	v_lshlrev_b32_e32 v58, 4, v38
	v_lshlrev_b32_e32 v59, 4, v39
	v_xad_u32 v47, v47, v97, v48
	v_add_u32_e32 v38, v49, v58
	v_add_u32_e32 v42, v49, v59
	v_or_b32_e32 v47, v47, v61
	v_add_f32_e32 v55, 1.0, v41
	s_waitcnt lgkmcnt(0)
	s_barrier
	ds_read_b128 v[38:41], v38
	ds_read_b128 v[42:45], v42
	v_add_u32_e32 v51, 0, v47
	ds_read_u16 v65, v98
	ds_read_u16 v52, v51
	v_or_b32_e32 v47, 2, v62
	v_or_b32_e32 v62, 3, v62
	v_bitop3_b32 v46, v54, v46, 12 bitop3:0x36
	s_waitcnt lgkmcnt(1)
	v_lshlrev_b32_e32 v90, 16, v65
	v_lshlrev_b32_e32 v65, 8, v62
	v_lshlrev_b32_e32 v62, 4, v62
	v_lshlrev_b32_e32 v48, 8, v47
	v_lshlrev_b32_e32 v47, 4, v47
	v_xad_u32 v62, v62, v97, v65
	v_lshlrev_b32_e32 v60, 4, v46
	v_xad_u32 v47, v47, v97, v48
	v_or_b32_e32 v62, v62, v61
	v_add_u32_e32 v50, v49, v57
	v_add_u32_e32 v46, v49, v60
	v_or_b32_e32 v47, v47, v61
	v_add_u32_e32 v62, 0, v62
	v_add_u32_e32 v66, 0, v47
	ds_read_b128 v[46:49], v46
	ds_read_u16 v67, v66 offset:32768
	ds_read_u16 v68, v51 offset:32768
	s_waitcnt lgkmcnt(3)
	v_lshlrev_b32_e32 v91, 16, v52
	ds_read_b128 v[50:53], v50
	ds_read_u16 v69, v98 offset:32768
	ds_read_u16 v65, v62
	v_cmp_gt_f32_e32 vcc, s45, v55
	ds_read_u16 v66, v66
	ds_read_u16 v62, v62 offset:32768
	s_mov_b32 s2, 0x3f317217
	v_cmp_eq_u32_e64 s[6:7], 2, v54
	s_waitcnt lgkmcnt(2)
	v_lshlrev_b32_e32 v89, 16, v65
	v_cndmask_b32_e64 v65, 0, 32, vcc
	v_ldexp_f32 v55, v55, v65
	v_log_f32_e32 v55, v55
	s_waitcnt lgkmcnt(0)
	v_lshlrev_b32_e32 v81, 16, v62
	v_cmp_lt_u32_e64 s[8:9], 1, v54
	v_lshlrev_b32_e32 v83, 16, v68
	v_mul_f32_e32 v62, 0x3f317217, v55
	v_fma_f32 v62, v55, s2, -v62
	v_fmac_f32_e32 v62, 0x3377d1cf, v55
	s_mov_b32 s2, 0x7f800000
	v_fmac_f32_e32 v62, 0x3f317217, v55
	v_cmp_lt_f32_e64 s[2:3], |v55|, s2
	v_lshlrev_b32_e32 v82, 16, v69
	v_lshlrev_b32_e32 v88, 16, v66
	v_cndmask_b32_e64 v55, v55, v62, s[2:3]
	v_cndmask_b32_e32 v62, 0, v241, vcc
	v_cmp_eq_u32_e32 vcc, 0, v54
	v_or_b32_e32 v54, v56, v60
	s_add_i32 s2, 0, 0x1000
	v_add_u32_e32 v100, s2, v54
	v_or_b32_e32 v54, v56, v59
	v_add_u32_e32 v101, s2, v54
	v_or_b32_e32 v54, v56, v58
	v_add_u32_e32 v102, s2, v54
	v_or_b32_e32 v54, v56, v57
	v_sub_f32_e32 v55, v55, v62
	v_add_u32_e32 v103, s2, v54
	v_or_b32_e32 v54, v63, v61
	v_lshlrev_b32_e32 v80, 16, v67
	v_mul_f32_e32 v99, 0xc1000000, v55
	v_add_u32_e32 v104, 0, v54
	v_or_b32_e32 v105, 0x120, v64
	s_branch .LBB0_596
